# v022 with the six GEMM K-loop heads aligned to 64 bytes (phase pin)
# speedup vs baseline: 1.0039x; 1.0017x over previous
.LBB0_126:
	s_ashr_i32 s29, s28, 31
	s_lshl_b64 s[6:7], s[28:29], 21
	v_cmp_lt_i64_e32 vcc, s[34:35], v[142:143]
	s_add_u32 s34, s70, s6
	s_addc_u32 s35, s71, s7
	s_and_b64 s[6:7], vcc, exec
	s_cselect_b32 s6, s35, s39
	s_cselect_b32 s7, s34, s38
	s_ashr_i32 s27, s26, 31
	s_lshl_b64 s[36:37], s[26:27], 21
	s_add_u32 s36, s58, s36
	s_addc_u32 s37, s59, s37
	s_and_b64 s[42:43], vcc, exec
	s_cselect_b32 s9, s37, s41
	s_cselect_b32 s11, s36, s40
	s_add_u32 s38, s38, 0x100080
	s_addc_u32 s39, s39, 0
	s_add_u32 s27, s40, 0x100
	v_mov_b32_e32 v0, 0
	s_addc_u32 s29, s41, 0
	s_mov_b32 s54, -2
	v_mov_b32_e32 v1, v0
	v_mov_b32_e32 v2, v0
	v_mov_b32_e32 v3, v0
	v_mov_b32_e32 v4, v0
	v_mov_b32_e32 v5, v0
	v_mov_b32_e32 v6, v0
	v_mov_b32_e32 v7, v0
	v_mov_b32_e32 v16, v0
	v_mov_b32_e32 v17, v0
	v_mov_b32_e32 v18, v0
	v_mov_b32_e32 v19, v0
	v_mov_b32_e32 v20, v0
	v_mov_b32_e32 v21, v0
	v_mov_b32_e32 v22, v0
	v_mov_b32_e32 v23, v0
	v_mov_b32_e32 v32, v0
	v_mov_b32_e32 v33, v0
	v_mov_b32_e32 v34, v0
	v_mov_b32_e32 v35, v0
	v_mov_b32_e32 v36, v0
	v_mov_b32_e32 v37, v0
	v_mov_b32_e32 v38, v0
	v_mov_b32_e32 v39, v0
	v_mov_b32_e32 v48, v0
	v_mov_b32_e32 v49, v0
	v_mov_b32_e32 v50, v0
	v_mov_b32_e32 v51, v0
	v_mov_b32_e32 v52, v0
	v_mov_b32_e32 v53, v0
	v_mov_b32_e32 v54, v0
	v_mov_b32_e32 v55, v0
	v_mov_b32_e32 v8, v0
	v_mov_b32_e32 v9, v0
	v_mov_b32_e32 v10, v0
	v_mov_b32_e32 v11, v0
	v_mov_b32_e32 v12, v0
	v_mov_b32_e32 v13, v0
	v_mov_b32_e32 v14, v0
	v_mov_b32_e32 v15, v0
	v_mov_b32_e32 v24, v0
	v_mov_b32_e32 v25, v0
	v_mov_b32_e32 v26, v0
	v_mov_b32_e32 v27, v0
	v_mov_b32_e32 v28, v0
	v_mov_b32_e32 v29, v0
	v_mov_b32_e32 v30, v0
	v_mov_b32_e32 v31, v0
	v_mov_b32_e32 v40, v0
	v_mov_b32_e32 v41, v0
	v_mov_b32_e32 v42, v0
	v_mov_b32_e32 v43, v0
	v_mov_b32_e32 v44, v0
	v_mov_b32_e32 v45, v0
	v_mov_b32_e32 v46, v0
	v_mov_b32_e32 v47, v0
	v_mov_b32_e32 v56, v0
	v_mov_b32_e32 v57, v0
	v_mov_b32_e32 v58, v0
	v_mov_b32_e32 v59, v0
	v_mov_b32_e32 v60, v0
	v_mov_b32_e32 v61, v0
	v_mov_b32_e32 v62, v0
	v_mov_b32_e32 v63, v0
	v_mov_b32_e32 v64, v0
	v_mov_b32_e32 v65, v0
	v_mov_b32_e32 v66, v0
	v_mov_b32_e32 v67, v0
	v_mov_b32_e32 v68, v0
	v_mov_b32_e32 v69, v0
	v_mov_b32_e32 v70, v0
	v_mov_b32_e32 v71, v0
	v_mov_b32_e32 v80, v0
	v_mov_b32_e32 v81, v0
	v_mov_b32_e32 v82, v0
	v_mov_b32_e32 v83, v0
	v_mov_b32_e32 v84, v0
	v_mov_b32_e32 v85, v0
	v_mov_b32_e32 v86, v0
	v_mov_b32_e32 v87, v0
	v_mov_b32_e32 v96, v0
	v_mov_b32_e32 v97, v0
	v_mov_b32_e32 v98, v0
	v_mov_b32_e32 v99, v0
	v_mov_b32_e32 v100, v0
	v_mov_b32_e32 v101, v0
	v_mov_b32_e32 v102, v0
	v_mov_b32_e32 v103, v0
	v_mov_b32_e32 v112, v0
	v_mov_b32_e32 v113, v0
	v_mov_b32_e32 v114, v0
	v_mov_b32_e32 v115, v0
	v_mov_b32_e32 v116, v0
	v_mov_b32_e32 v117, v0
	v_mov_b32_e32 v118, v0
	v_mov_b32_e32 v119, v0
	v_mov_b32_e32 v72, v0
	v_mov_b32_e32 v73, v0
	v_mov_b32_e32 v74, v0
	v_mov_b32_e32 v75, v0
	v_mov_b32_e32 v76, v0
	v_mov_b32_e32 v77, v0
	v_mov_b32_e32 v78, v0
	v_mov_b32_e32 v79, v0
	v_mov_b32_e32 v88, v0
	v_mov_b32_e32 v89, v0
	v_mov_b32_e32 v90, v0
	v_mov_b32_e32 v91, v0
	v_mov_b32_e32 v92, v0
	v_mov_b32_e32 v93, v0
	v_mov_b32_e32 v94, v0
	v_mov_b32_e32 v95, v0
	v_mov_b32_e32 v104, v0
	v_mov_b32_e32 v105, v0
	v_mov_b32_e32 v106, v0
	v_mov_b32_e32 v107, v0
	v_mov_b32_e32 v108, v0
	v_mov_b32_e32 v109, v0
	v_mov_b32_e32 v110, v0
	v_mov_b32_e32 v111, v0
	v_mov_b32_e32 v120, v0
	v_mov_b32_e32 v121, v0
	v_mov_b32_e32 v122, v0
	v_mov_b32_e32 v123, v0
	v_mov_b32_e32 v124, v0
	v_mov_b32_e32 v125, v0
	v_mov_b32_e32 v126, v0
	v_mov_b32_e32 v127, v0
	.p2align 6

.LBB0_300:
	s_ashr_i32 s37, s36, 31
	s_lshl_b64 s[40:41], s[36:37], 19
	s_add_u32 s40, s30, s40
	s_addc_u32 s41, s31, s41
	s_and_b64 s[46:47], s[8:9], exec
	s_cselect_b32 s37, s41, s45
	s_cselect_b32 s62, s40, s44
	s_add_u32 s63, s44, 0x100
	v_mov_b32_e32 v0, 0
	s_addc_u32 s82, s45, 0
	s_mov_b32 s83, -2
	v_mov_b32_e32 v1, v0
	v_mov_b32_e32 v2, v0
	v_mov_b32_e32 v3, v0
	v_mov_b32_e32 v4, v0
	v_mov_b32_e32 v5, v0
	v_mov_b32_e32 v6, v0
	v_mov_b32_e32 v7, v0
	v_mov_b32_e32 v12, v0
	v_mov_b32_e32 v13, v0
	v_mov_b32_e32 v14, v0
	v_mov_b32_e32 v15, v0
	v_mov_b32_e32 v20, v0
	v_mov_b32_e32 v21, v0
	v_mov_b32_e32 v22, v0
	v_mov_b32_e32 v23, v0
	v_mov_b32_e32 v28, v0
	v_mov_b32_e32 v29, v0
	v_mov_b32_e32 v30, v0
	v_mov_b32_e32 v31, v0
	v_mov_b32_e32 v36, v0
	v_mov_b32_e32 v37, v0
	v_mov_b32_e32 v38, v0
	v_mov_b32_e32 v39, v0
	v_mov_b32_e32 v44, v0
	v_mov_b32_e32 v45, v0
	v_mov_b32_e32 v46, v0
	v_mov_b32_e32 v47, v0
	v_mov_b32_e32 v52, v0
	v_mov_b32_e32 v53, v0
	v_mov_b32_e32 v54, v0
	v_mov_b32_e32 v55, v0
	v_mov_b32_e32 v8, v0
	v_mov_b32_e32 v9, v0
	v_mov_b32_e32 v10, v0
	v_mov_b32_e32 v11, v0
	v_mov_b32_e32 v16, v0
	v_mov_b32_e32 v17, v0
	v_mov_b32_e32 v18, v0
	v_mov_b32_e32 v19, v0
	v_mov_b32_e32 v24, v0
	v_mov_b32_e32 v25, v0
	v_mov_b32_e32 v26, v0
	v_mov_b32_e32 v27, v0
	v_mov_b32_e32 v32, v0
	v_mov_b32_e32 v33, v0
	v_mov_b32_e32 v34, v0
	v_mov_b32_e32 v35, v0
	v_mov_b32_e32 v40, v0
	v_mov_b32_e32 v41, v0
	v_mov_b32_e32 v42, v0
	v_mov_b32_e32 v43, v0
	v_mov_b32_e32 v48, v0
	v_mov_b32_e32 v49, v0
	v_mov_b32_e32 v50, v0
	v_mov_b32_e32 v51, v0
	v_mov_b32_e32 v56, v0
	v_mov_b32_e32 v57, v0
	v_mov_b32_e32 v58, v0
	v_mov_b32_e32 v59, v0
	v_mov_b32_e32 v60, v0
	v_mov_b32_e32 v61, v0
	v_mov_b32_e32 v62, v0
	v_mov_b32_e32 v63, v0
	v_mov_b32_e32 v64, v0
	v_mov_b32_e32 v65, v0
	v_mov_b32_e32 v66, v0
	v_mov_b32_e32 v67, v0
	v_mov_b32_e32 v68, v0
	v_mov_b32_e32 v69, v0
	v_mov_b32_e32 v70, v0
	v_mov_b32_e32 v71, v0
	v_mov_b32_e32 v76, v0
	v_mov_b32_e32 v77, v0
	v_mov_b32_e32 v78, v0
	v_mov_b32_e32 v79, v0
	v_mov_b32_e32 v84, v0
	v_mov_b32_e32 v85, v0
	v_mov_b32_e32 v86, v0
	v_mov_b32_e32 v87, v0
	v_mov_b32_e32 v92, v0
	v_mov_b32_e32 v93, v0
	v_mov_b32_e32 v94, v0
	v_mov_b32_e32 v95, v0
	v_mov_b32_e32 v100, v0
	v_mov_b32_e32 v101, v0
	v_mov_b32_e32 v102, v0
	v_mov_b32_e32 v103, v0
	v_mov_b32_e32 v108, v0
	v_mov_b32_e32 v109, v0
	v_mov_b32_e32 v110, v0
	v_mov_b32_e32 v111, v0
	v_mov_b32_e32 v116, v0
	v_mov_b32_e32 v117, v0
	v_mov_b32_e32 v118, v0
	v_mov_b32_e32 v119, v0
	v_mov_b32_e32 v72, v0
	v_mov_b32_e32 v73, v0
	v_mov_b32_e32 v74, v0
	v_mov_b32_e32 v75, v0
	v_mov_b32_e32 v80, v0
	v_mov_b32_e32 v81, v0
	v_mov_b32_e32 v82, v0
	v_mov_b32_e32 v83, v0
	v_mov_b32_e32 v88, v0
	v_mov_b32_e32 v89, v0
	v_mov_b32_e32 v90, v0
	v_mov_b32_e32 v91, v0
	v_mov_b32_e32 v96, v0
	v_mov_b32_e32 v97, v0
	v_mov_b32_e32 v98, v0
	v_mov_b32_e32 v99, v0
	v_mov_b32_e32 v104, v0
	v_mov_b32_e32 v105, v0
	v_mov_b32_e32 v106, v0
	v_mov_b32_e32 v107, v0
	v_mov_b32_e32 v112, v0
	v_mov_b32_e32 v113, v0
	v_mov_b32_e32 v114, v0
	v_mov_b32_e32 v115, v0
	v_mov_b32_e32 v120, v0
	v_mov_b32_e32 v121, v0
	v_mov_b32_e32 v122, v0
	v_mov_b32_e32 v123, v0
	v_mov_b32_e32 v124, v0
	v_mov_b32_e32 v125, v0
	v_mov_b32_e32 v126, v0
	v_mov_b32_e32 v127, v0
	.p2align 6

.LBB0_324:
	s_ashr_i32 s41, s40, 31
	s_lshl_b64 s[44:45], s[40:41], 18
	s_add_u32 s44, s22, s44
	s_addc_u32 s45, s23, s45
	s_and_b64 s[50:51], s[8:9], exec
	s_cselect_b32 s41, s45, s49
	s_cselect_b32 s62, s44, s48
	s_add_u32 s63, s48, 0x100
	v_mov_b32_e32 v0, 0
	s_addc_u32 s90, s49, 0
	s_mov_b32 s91, -2
	v_mov_b32_e32 v1, v0
	v_mov_b32_e32 v2, v0
	v_mov_b32_e32 v3, v0
	v_mov_b32_e32 v4, v0
	v_mov_b32_e32 v5, v0
	v_mov_b32_e32 v6, v0
	v_mov_b32_e32 v7, v0
	v_mov_b32_e32 v12, v0
	v_mov_b32_e32 v13, v0
	v_mov_b32_e32 v14, v0
	v_mov_b32_e32 v15, v0
	v_mov_b32_e32 v20, v0
	v_mov_b32_e32 v21, v0
	v_mov_b32_e32 v22, v0
	v_mov_b32_e32 v23, v0
	v_mov_b32_e32 v28, v0
	v_mov_b32_e32 v29, v0
	v_mov_b32_e32 v30, v0
	v_mov_b32_e32 v31, v0
	v_mov_b32_e32 v36, v0
	v_mov_b32_e32 v37, v0
	v_mov_b32_e32 v38, v0
	v_mov_b32_e32 v39, v0
	v_mov_b32_e32 v44, v0
	v_mov_b32_e32 v45, v0
	v_mov_b32_e32 v46, v0
	v_mov_b32_e32 v47, v0
	v_mov_b32_e32 v52, v0
	v_mov_b32_e32 v53, v0
	v_mov_b32_e32 v54, v0
	v_mov_b32_e32 v55, v0
	v_mov_b32_e32 v8, v0
	v_mov_b32_e32 v9, v0
	v_mov_b32_e32 v10, v0
	v_mov_b32_e32 v11, v0
	v_mov_b32_e32 v16, v0
	v_mov_b32_e32 v17, v0
	v_mov_b32_e32 v18, v0
	v_mov_b32_e32 v19, v0
	v_mov_b32_e32 v24, v0
	v_mov_b32_e32 v25, v0
	v_mov_b32_e32 v26, v0
	v_mov_b32_e32 v27, v0
	v_mov_b32_e32 v32, v0
	v_mov_b32_e32 v33, v0
	v_mov_b32_e32 v34, v0
	v_mov_b32_e32 v35, v0
	v_mov_b32_e32 v40, v0
	v_mov_b32_e32 v41, v0
	v_mov_b32_e32 v42, v0
	v_mov_b32_e32 v43, v0
	v_mov_b32_e32 v48, v0
	v_mov_b32_e32 v49, v0
	v_mov_b32_e32 v50, v0
	v_mov_b32_e32 v51, v0
	v_mov_b32_e32 v56, v0
	v_mov_b32_e32 v57, v0
	v_mov_b32_e32 v58, v0
	v_mov_b32_e32 v59, v0
	v_mov_b32_e32 v60, v0
	v_mov_b32_e32 v61, v0
	v_mov_b32_e32 v62, v0
	v_mov_b32_e32 v63, v0
	v_mov_b32_e32 v64, v0
	v_mov_b32_e32 v65, v0
	v_mov_b32_e32 v66, v0
	v_mov_b32_e32 v67, v0
	v_mov_b32_e32 v68, v0
	v_mov_b32_e32 v69, v0
	v_mov_b32_e32 v70, v0
	v_mov_b32_e32 v71, v0
	v_mov_b32_e32 v80, v0
	v_mov_b32_e32 v81, v0
	v_mov_b32_e32 v82, v0
	v_mov_b32_e32 v83, v0
	v_mov_b32_e32 v84, v0
	v_mov_b32_e32 v85, v0
	v_mov_b32_e32 v86, v0
	v_mov_b32_e32 v87, v0
	v_mov_b32_e32 v96, v0
	v_mov_b32_e32 v97, v0
	v_mov_b32_e32 v98, v0
	v_mov_b32_e32 v99, v0
	v_mov_b32_e32 v100, v0
	v_mov_b32_e32 v101, v0
	v_mov_b32_e32 v102, v0
	v_mov_b32_e32 v103, v0
	v_mov_b32_e32 v112, v0
	v_mov_b32_e32 v113, v0
	v_mov_b32_e32 v114, v0
	v_mov_b32_e32 v115, v0
	v_mov_b32_e32 v116, v0
	v_mov_b32_e32 v117, v0
	v_mov_b32_e32 v118, v0
	v_mov_b32_e32 v119, v0
	v_mov_b32_e32 v72, v0
	v_mov_b32_e32 v73, v0
	v_mov_b32_e32 v74, v0
	v_mov_b32_e32 v75, v0
	v_mov_b32_e32 v76, v0
	v_mov_b32_e32 v77, v0
	v_mov_b32_e32 v78, v0
	v_mov_b32_e32 v79, v0
	v_mov_b32_e32 v88, v0
	v_mov_b32_e32 v89, v0
	v_mov_b32_e32 v90, v0
	v_mov_b32_e32 v91, v0
	v_mov_b32_e32 v92, v0
	v_mov_b32_e32 v93, v0
	v_mov_b32_e32 v94, v0
	v_mov_b32_e32 v95, v0
	v_mov_b32_e32 v104, v0
	v_mov_b32_e32 v105, v0
	v_mov_b32_e32 v106, v0
	v_mov_b32_e32 v107, v0
	v_mov_b32_e32 v108, v0
	v_mov_b32_e32 v109, v0
	v_mov_b32_e32 v110, v0
	v_mov_b32_e32 v111, v0
	v_mov_b32_e32 v120, v0
	v_mov_b32_e32 v121, v0
	v_mov_b32_e32 v122, v0
	v_mov_b32_e32 v123, v0
	v_mov_b32_e32 v124, v0
	v_mov_b32_e32 v125, v0
	v_mov_b32_e32 v126, v0
	v_mov_b32_e32 v127, v0
	.p2align 6

.LBB0_513:
	s_ashr_i32 s27, s26, 31
	s_lshl_b64 s[6:7], s[26:27], 21
	v_cmp_lt_i64_e32 vcc, s[28:29], v[156:157]
	s_add_u32 s28, s70, s6
	s_addc_u32 s29, s71, s7
	s_and_b64 s[6:7], vcc, exec
	s_cselect_b32 s6, s29, s39
	s_cselect_b32 s7, s28, s38
	s_ashr_i32 s25, s24, 31
	s_lshl_b64 s[30:31], s[24:25], 21
	s_add_u32 s30, s14, s30
	s_addc_u32 s31, s15, s31
	s_and_b64 s[42:43], vcc, exec
	s_cselect_b32 s25, s31, s41
	s_cselect_b32 s27, s30, s40
	s_add_u32 s38, s38, 0x100080
	s_addc_u32 s39, s39, 0
	s_add_u32 s35, s40, 0x100
	v_mov_b32_e32 v0, 0
	s_addc_u32 s55, s41, 0
	s_mov_b32 s61, -2
	s_waitcnt lgkmcnt(0)
	v_mov_b32_e32 v1, v0
	v_mov_b32_e32 v2, v0
	v_mov_b32_e32 v3, v0
	v_mov_b32_e32 v4, v0
	v_mov_b32_e32 v5, v0
	v_mov_b32_e32 v6, v0
	v_mov_b32_e32 v7, v0
	v_mov_b32_e32 v16, v0
	v_mov_b32_e32 v17, v0
	v_mov_b32_e32 v18, v0
	v_mov_b32_e32 v19, v0
	v_mov_b32_e32 v20, v0
	v_mov_b32_e32 v21, v0
	v_mov_b32_e32 v22, v0
	v_mov_b32_e32 v23, v0
	v_mov_b32_e32 v32, v0
	v_mov_b32_e32 v33, v0
	v_mov_b32_e32 v34, v0
	v_mov_b32_e32 v35, v0
	v_mov_b32_e32 v36, v0
	v_mov_b32_e32 v37, v0
	v_mov_b32_e32 v38, v0
	v_mov_b32_e32 v39, v0
	v_mov_b32_e32 v48, v0
	v_mov_b32_e32 v49, v0
	v_mov_b32_e32 v50, v0
	v_mov_b32_e32 v51, v0
	v_mov_b32_e32 v52, v0
	v_mov_b32_e32 v53, v0
	v_mov_b32_e32 v54, v0
	v_mov_b32_e32 v55, v0
	v_mov_b32_e32 v8, v0
	v_mov_b32_e32 v9, v0
	v_mov_b32_e32 v10, v0
	v_mov_b32_e32 v11, v0
	v_mov_b32_e32 v12, v0
	v_mov_b32_e32 v13, v0
	v_mov_b32_e32 v14, v0
	v_mov_b32_e32 v15, v0
	v_mov_b32_e32 v24, v0
	v_mov_b32_e32 v25, v0
	v_mov_b32_e32 v26, v0
	v_mov_b32_e32 v27, v0
	v_mov_b32_e32 v28, v0
	v_mov_b32_e32 v29, v0
	v_mov_b32_e32 v30, v0
	v_mov_b32_e32 v31, v0
	v_mov_b32_e32 v40, v0
	v_mov_b32_e32 v41, v0
	v_mov_b32_e32 v42, v0
	v_mov_b32_e32 v43, v0
	v_mov_b32_e32 v44, v0
	v_mov_b32_e32 v45, v0
	v_mov_b32_e32 v46, v0
	v_mov_b32_e32 v47, v0
	v_mov_b32_e32 v56, v0
	v_mov_b32_e32 v57, v0
	v_mov_b32_e32 v58, v0
	v_mov_b32_e32 v59, v0
	v_mov_b32_e32 v60, v0
	v_mov_b32_e32 v61, v0
	v_mov_b32_e32 v62, v0
	v_mov_b32_e32 v63, v0
	v_mov_b32_e32 v64, v0
	v_mov_b32_e32 v65, v0
	v_mov_b32_e32 v66, v0
	v_mov_b32_e32 v67, v0
	v_mov_b32_e32 v68, v0
	v_mov_b32_e32 v69, v0
	v_mov_b32_e32 v70, v0
	v_mov_b32_e32 v71, v0
	v_mov_b32_e32 v80, v0
	v_mov_b32_e32 v81, v0
	v_mov_b32_e32 v82, v0
	v_mov_b32_e32 v83, v0
	v_mov_b32_e32 v84, v0
	v_mov_b32_e32 v85, v0
	v_mov_b32_e32 v86, v0
	v_mov_b32_e32 v87, v0
	v_mov_b32_e32 v96, v0
	v_mov_b32_e32 v97, v0
	v_mov_b32_e32 v98, v0
	v_mov_b32_e32 v99, v0
	v_mov_b32_e32 v100, v0
	v_mov_b32_e32 v101, v0
	v_mov_b32_e32 v102, v0
	v_mov_b32_e32 v103, v0
	v_mov_b32_e32 v112, v0
	v_mov_b32_e32 v113, v0
	v_mov_b32_e32 v114, v0
	v_mov_b32_e32 v115, v0
	v_mov_b32_e32 v116, v0
	v_mov_b32_e32 v117, v0
	v_mov_b32_e32 v118, v0
	v_mov_b32_e32 v119, v0
	v_mov_b32_e32 v72, v0
	v_mov_b32_e32 v73, v0
	v_mov_b32_e32 v74, v0
	v_mov_b32_e32 v75, v0
	v_mov_b32_e32 v76, v0
	v_mov_b32_e32 v77, v0
	v_mov_b32_e32 v78, v0
	v_mov_b32_e32 v79, v0
	v_mov_b32_e32 v88, v0
	v_mov_b32_e32 v89, v0
	v_mov_b32_e32 v90, v0
	v_mov_b32_e32 v91, v0
	v_mov_b32_e32 v92, v0
	v_mov_b32_e32 v93, v0
	v_mov_b32_e32 v94, v0
	v_mov_b32_e32 v95, v0
	v_mov_b32_e32 v104, v0
	v_mov_b32_e32 v105, v0
	v_mov_b32_e32 v106, v0
	v_mov_b32_e32 v107, v0
	v_mov_b32_e32 v108, v0
	v_mov_b32_e32 v109, v0
	v_mov_b32_e32 v110, v0
	v_mov_b32_e32 v111, v0
	v_mov_b32_e32 v120, v0
	v_mov_b32_e32 v121, v0
	v_mov_b32_e32 v122, v0
	v_mov_b32_e32 v123, v0
	v_mov_b32_e32 v124, v0
	v_mov_b32_e32 v125, v0
	v_mov_b32_e32 v126, v0
	v_mov_b32_e32 v127, v0
	.p2align 6

.LBB0_603:
	s_ashr_i32 s41, s40, 31
	s_lshl_b64 s[4:5], s[40:41], 21
	s_add_u32 s42, s56, s4
	v_cmp_lt_i64_e64 s[8:9], s[8:9], v[156:157]
	s_addc_u32 s43, s57, s5
	s_and_b64 s[4:5], s[8:9], exec
	s_cselect_b32 s4, s43, s11
	s_cselect_b32 s5, s42, s10
	s_ashr_i32 s39, s38, 31
	s_lshl_b64 s[6:7], s[38:39], 21
	s_add_u32 s44, s16, s6
	s_addc_u32 s45, s17, s7
	s_and_b64 s[6:7], s[8:9], exec
	s_cselect_b32 s6, s45, s47
	s_cselect_b32 s7, s44, s46
	s_add_u32 s10, s10, 0x100080
	s_addc_u32 s11, s11, 0
	s_add_u32 s13, s46, 0x100
	v_mov_b32_e32 v0, 0
	s_addc_u32 s15, s47, 0
	s_mov_b32 s39, -2
	v_mov_b32_e32 v1, v0
	v_mov_b32_e32 v2, v0
	v_mov_b32_e32 v3, v0
	v_mov_b32_e32 v4, v0
	v_mov_b32_e32 v5, v0
	v_mov_b32_e32 v6, v0
	v_mov_b32_e32 v7, v0
	v_mov_b32_e32 v24, v0
	v_mov_b32_e32 v25, v0
	v_mov_b32_e32 v26, v0
	v_mov_b32_e32 v27, v0
	v_mov_b32_e32 v28, v0
	v_mov_b32_e32 v29, v0
	v_mov_b32_e32 v30, v0
	v_mov_b32_e32 v31, v0
	v_mov_b32_e32 v48, v0
	v_mov_b32_e32 v49, v0
	v_mov_b32_e32 v50, v0
	v_mov_b32_e32 v51, v0
	v_mov_b32_e32 v52, v0
	v_mov_b32_e32 v53, v0
	v_mov_b32_e32 v54, v0
	v_mov_b32_e32 v55, v0
	v_mov_b32_e32 v64, v0
	v_mov_b32_e32 v65, v0
	v_mov_b32_e32 v66, v0
	v_mov_b32_e32 v67, v0
	v_mov_b32_e32 v68, v0
	v_mov_b32_e32 v69, v0
	v_mov_b32_e32 v70, v0
	v_mov_b32_e32 v71, v0
	v_mov_b32_e32 v8, v0
	v_mov_b32_e32 v9, v0
	v_mov_b32_e32 v10, v0
	v_mov_b32_e32 v11, v0
	v_mov_b32_e32 v12, v0
	v_mov_b32_e32 v13, v0
	v_mov_b32_e32 v14, v0
	v_mov_b32_e32 v15, v0
	v_mov_b32_e32 v40, v0
	v_mov_b32_e32 v41, v0
	v_mov_b32_e32 v42, v0
	v_mov_b32_e32 v43, v0
	v_mov_b32_e32 v44, v0
	v_mov_b32_e32 v45, v0
	v_mov_b32_e32 v46, v0
	v_mov_b32_e32 v47, v0
	v_mov_b32_e32 v56, v0
	v_mov_b32_e32 v57, v0
	v_mov_b32_e32 v58, v0
	v_mov_b32_e32 v59, v0
	v_mov_b32_e32 v60, v0
	v_mov_b32_e32 v61, v0
	v_mov_b32_e32 v62, v0
	v_mov_b32_e32 v63, v0
	v_mov_b32_e32 v72, v0
	v_mov_b32_e32 v73, v0
	v_mov_b32_e32 v74, v0
	v_mov_b32_e32 v75, v0
	v_mov_b32_e32 v76, v0
	v_mov_b32_e32 v77, v0
	v_mov_b32_e32 v78, v0
	v_mov_b32_e32 v79, v0
	v_mov_b32_e32 v80, v0
	v_mov_b32_e32 v81, v0
	v_mov_b32_e32 v82, v0
	v_mov_b32_e32 v83, v0
	v_mov_b32_e32 v84, v0
	v_mov_b32_e32 v85, v0
	v_mov_b32_e32 v86, v0
	v_mov_b32_e32 v87, v0
	v_mov_b32_e32 v96, v0
	v_mov_b32_e32 v97, v0
	v_mov_b32_e32 v98, v0
	v_mov_b32_e32 v99, v0
	v_mov_b32_e32 v100, v0
	v_mov_b32_e32 v101, v0
	v_mov_b32_e32 v102, v0
	v_mov_b32_e32 v103, v0
	v_mov_b32_e32 v112, v0
	v_mov_b32_e32 v113, v0
	v_mov_b32_e32 v114, v0
	v_mov_b32_e32 v115, v0
	v_mov_b32_e32 v116, v0
	v_mov_b32_e32 v117, v0
	v_mov_b32_e32 v118, v0
	v_mov_b32_e32 v119, v0
	v_mov_b32_e32 v128, v0
	v_mov_b32_e32 v129, v0
	v_mov_b32_e32 v130, v0
	v_mov_b32_e32 v131, v0
	v_mov_b32_e32 v132, v0
	v_mov_b32_e32 v133, v0
	v_mov_b32_e32 v134, v0
	v_mov_b32_e32 v135, v0
	v_mov_b32_e32 v88, v0
	v_mov_b32_e32 v89, v0
	v_mov_b32_e32 v90, v0
	v_mov_b32_e32 v91, v0
	v_mov_b32_e32 v92, v0
	v_mov_b32_e32 v93, v0
	v_mov_b32_e32 v94, v0
	v_mov_b32_e32 v95, v0
	v_mov_b32_e32 v104, v0
	v_mov_b32_e32 v105, v0
	v_mov_b32_e32 v106, v0
	v_mov_b32_e32 v107, v0
	v_mov_b32_e32 v108, v0
	v_mov_b32_e32 v109, v0
	v_mov_b32_e32 v110, v0
	v_mov_b32_e32 v111, v0
	v_mov_b32_e32 v120, v0
	v_mov_b32_e32 v121, v0
	v_mov_b32_e32 v122, v0
	v_mov_b32_e32 v123, v0
	v_mov_b32_e32 v124, v0
	v_mov_b32_e32 v125, v0
	v_mov_b32_e32 v126, v0
	v_mov_b32_e32 v127, v0
	v_mov_b32_e32 v136, v0
	v_mov_b32_e32 v137, v0
	v_mov_b32_e32 v138, v0
	v_mov_b32_e32 v139, v0
	v_mov_b32_e32 v140, v0
	v_mov_b32_e32 v141, v0
	v_mov_b32_e32 v142, v0
	v_mov_b32_e32 v143, v0
	.p2align 6

.LBB0_980:
	s_ashr_i32 s15, s14, 31
	v_cmp_lt_i64_e32 vcc, s[16:17], v[148:149]
	s_lshl_b64 s[16:17], s[14:15], 23
	s_add_u32 s16, s4, s16
	s_addc_u32 s17, s5, s17
	s_and_b64 s[18:19], vcc, exec
	s_cselect_b32 s15, s17, s25
	s_cselect_b32 s21, s16, s24
	s_ashr_i32 s13, s12, 31
	s_lshl_b64 s[18:19], s[12:13], 21
	s_add_u32 s18, s66, s18
	s_addc_u32 s19, s67, s19
	s_and_b64 s[28:29], vcc, exec
	s_cselect_b32 s13, s19, s27
	s_cselect_b32 s44, s18, s26
	s_add_u32 s24, s24, 0x400080
	s_addc_u32 s25, s25, 0
	s_add_u32 s45, s26, 0x100
	v_mov_b32_e32 v0, 0
	s_addc_u32 s46, s27, 0
	s_mov_b32 s47, -2
	s_waitcnt lgkmcnt(0)
	v_mov_b32_e32 v1, v0
	v_mov_b32_e32 v2, v0
	v_mov_b32_e32 v3, v0
	v_mov_b32_e32 v4, v0
	v_mov_b32_e32 v5, v0
	v_mov_b32_e32 v6, v0
	v_mov_b32_e32 v7, v0
	v_mov_b32_e32 v16, v0
	v_mov_b32_e32 v17, v0
	v_mov_b32_e32 v18, v0
	v_mov_b32_e32 v19, v0
	v_mov_b32_e32 v20, v0
	v_mov_b32_e32 v21, v0
	v_mov_b32_e32 v22, v0
	v_mov_b32_e32 v23, v0
	v_mov_b32_e32 v32, v0
	v_mov_b32_e32 v33, v0
	v_mov_b32_e32 v34, v0
	v_mov_b32_e32 v35, v0
	v_mov_b32_e32 v36, v0
	v_mov_b32_e32 v37, v0
	v_mov_b32_e32 v38, v0
	v_mov_b32_e32 v39, v0
	v_mov_b32_e32 v48, v0
	v_mov_b32_e32 v49, v0
	v_mov_b32_e32 v50, v0
	v_mov_b32_e32 v51, v0
	v_mov_b32_e32 v52, v0
	v_mov_b32_e32 v53, v0
	v_mov_b32_e32 v54, v0
	v_mov_b32_e32 v55, v0
	v_mov_b32_e32 v8, v0
	v_mov_b32_e32 v9, v0
	v_mov_b32_e32 v10, v0
	v_mov_b32_e32 v11, v0
	v_mov_b32_e32 v12, v0
	v_mov_b32_e32 v13, v0
	v_mov_b32_e32 v14, v0
	v_mov_b32_e32 v15, v0
	v_mov_b32_e32 v24, v0
	v_mov_b32_e32 v25, v0
	v_mov_b32_e32 v26, v0
	v_mov_b32_e32 v27, v0
	v_mov_b32_e32 v28, v0
	v_mov_b32_e32 v29, v0
	v_mov_b32_e32 v30, v0
	v_mov_b32_e32 v31, v0
	v_mov_b32_e32 v40, v0
	v_mov_b32_e32 v41, v0
	v_mov_b32_e32 v42, v0
	v_mov_b32_e32 v43, v0
	v_mov_b32_e32 v44, v0
	v_mov_b32_e32 v45, v0
	v_mov_b32_e32 v46, v0
	v_mov_b32_e32 v47, v0
	v_mov_b32_e32 v56, v0
	v_mov_b32_e32 v57, v0
	v_mov_b32_e32 v58, v0
	v_mov_b32_e32 v59, v0
	v_mov_b32_e32 v60, v0
	v_mov_b32_e32 v61, v0
	v_mov_b32_e32 v62, v0
	v_mov_b32_e32 v63, v0
	v_mov_b32_e32 v64, v0
	v_mov_b32_e32 v65, v0
	v_mov_b32_e32 v66, v0
	v_mov_b32_e32 v67, v0
	v_mov_b32_e32 v68, v0
	v_mov_b32_e32 v69, v0
	v_mov_b32_e32 v70, v0
	v_mov_b32_e32 v71, v0
	v_mov_b32_e32 v80, v0
	v_mov_b32_e32 v81, v0
	v_mov_b32_e32 v82, v0
	v_mov_b32_e32 v83, v0
	v_mov_b32_e32 v84, v0
	v_mov_b32_e32 v85, v0
	v_mov_b32_e32 v86, v0
	v_mov_b32_e32 v87, v0
	v_mov_b32_e32 v96, v0
	v_mov_b32_e32 v97, v0
	v_mov_b32_e32 v98, v0
	v_mov_b32_e32 v99, v0
	v_mov_b32_e32 v100, v0
	v_mov_b32_e32 v101, v0
	v_mov_b32_e32 v102, v0
	v_mov_b32_e32 v103, v0
	v_mov_b32_e32 v112, v0
	v_mov_b32_e32 v113, v0
	v_mov_b32_e32 v114, v0
	v_mov_b32_e32 v115, v0
	v_mov_b32_e32 v116, v0
	v_mov_b32_e32 v117, v0
	v_mov_b32_e32 v118, v0
	v_mov_b32_e32 v119, v0
	v_mov_b32_e32 v72, v0
	v_mov_b32_e32 v73, v0
	v_mov_b32_e32 v74, v0
	v_mov_b32_e32 v75, v0
	v_mov_b32_e32 v76, v0
	v_mov_b32_e32 v77, v0
	v_mov_b32_e32 v78, v0
	v_mov_b32_e32 v79, v0
	v_mov_b32_e32 v88, v0
	v_mov_b32_e32 v89, v0
	v_mov_b32_e32 v90, v0
	v_mov_b32_e32 v91, v0
	v_mov_b32_e32 v92, v0
	v_mov_b32_e32 v93, v0
	v_mov_b32_e32 v94, v0
	v_mov_b32_e32 v95, v0
	v_mov_b32_e32 v104, v0
	v_mov_b32_e32 v105, v0
	v_mov_b32_e32 v106, v0
	v_mov_b32_e32 v107, v0
	v_mov_b32_e32 v108, v0
	v_mov_b32_e32 v109, v0
	v_mov_b32_e32 v110, v0
	v_mov_b32_e32 v111, v0
	v_mov_b32_e32 v120, v0
	v_mov_b32_e32 v121, v0
	v_mov_b32_e32 v122, v0
	v_mov_b32_e32 v123, v0
	v_mov_b32_e32 v124, v0
	v_mov_b32_e32 v125, v0
	v_mov_b32_e32 v126, v0
	v_mov_b32_e32 v127, v0
	.p2align 6
